# mixer work queue: next claim atomic issued early (thread 0, at the start of context units and in the MLA epilogue), loop-back site only broadcasts it
# speedup vs baseline: 1.0114x; 1.0114x over previous
.LBB0_1193:
	s_mov_b32 s32, 0
	v_readlane_b32 s8, v252, 7
	v_readlane_b32 s9, v252, 8
	s_and_b64 s[8:9], s[8:9], s[14:15]
	s_and_b64 vcc, exec, s[8:9]
	s_mov_b32 s10, -1
	s_cbranch_vccnz .LBB0_1197
	s_barrier
	s_and_saveexec_b64 s[8:9], s[4:5]
	s_cbranch_execz .LBB0_1196
	s_lshl_b64 s[10:11], s[6:7], 2
	v_readlane_b32 s12, v252, 11
	s_add_u32 s10, s12, s10
	v_readlane_b32 s12, v252, 12
	s_addc_u32 s11, s12, s11
	v_mov_b64_e32 v[4:5], s[10:11]
	flat_atomic_add v4, v[4:5], v177 sc0
	s_waitcnt vmcnt(0) lgkmcnt(0)
	ds_write_b32 v178, v4

.LBB0_1216:
	s_mov_b64 s[98:99], exec
	s_mov_b64 exec, s[4:5]
	s_cbranch_execz .Lqp3
	v_readlane_b32 s8, v252, 23
	v_readlane_b32 s9, v252, 24
	s_nop 1
	v_mov_b64_e32 v[254:255], s[8:9]
	global_atomic_add v253, v[254:255], v177, off sc0
.Lqp3:
	s_mov_b64 exec, s[98:99]
	s_mov_b32 s32, 1
	s_nop 4
.Lqe3:
	v_mov_b32_e32 v4, v101
	s_nop 1
	v_permlane16_swap_b32_e32 v101, v4
	v_add_f32_e32 v4, v101, v4
	v_mov_b32_e32 v5, v4
	s_nop 1
	v_permlane32_swap_b32_e32 v4, v5
	v_add_f32_e32 v4, v4, v5
	v_div_scale_f32 v5, s[6:7], v4, v4, 1.0
	v_rcp_f32_e32 v6, v5
	v_lshlrev_b32_e32 v88, 1, v97
	v_fma_f32 v7, -v5, v6, 1.0
	v_fmac_f32_e32 v6, v7, v6
	v_div_scale_f32 v7, vcc, 1.0, v4, 1.0
	v_mul_f32_e32 v8, v7, v6
	v_fma_f32 v9, -v5, v8, v7
	v_fmac_f32_e32 v8, v9, v6
	v_fma_f32 v5, -v5, v8, v7
	v_div_fmas_f32 v5, v5, v6, v8
	v_lshlrev_b64 v[6:7], 11, v[92:93]
	v_div_fixup_f32 v4, v5, v4, 1.0
	v_lshl_add_u64 v[6:7], s[48:49], 0, v[6:7]
	v_lshl_add_u64 v[6:7], v[6:7], 0, s[44:45]
	v_pk_mul_f32 v[8:9], v[68:69], v[4:5] op_sel_hi:[1,0]
	v_pk_mul_f32 v[10:11], v[70:71], v[4:5] op_sel_hi:[1,0]
	v_lshl_add_u64 v[6:7], v[6:7], 0, v[88:89]
	v_cvt_pk_bf16_f32 v8, v8, v9
	v_cvt_pk_bf16_f32 v9, v10, v11
	flat_store_dwordx2 v[6:7], v[8:9]
	v_pk_mul_f32 v[8:9], v[64:65], v[4:5] op_sel_hi:[1,0]
	v_pk_mul_f32 v[10:11], v[66:67], v[4:5] op_sel_hi:[1,0]
	v_cvt_pk_bf16_f32 v8, v8, v9
	v_cvt_pk_bf16_f32 v9, v10, v11
	flat_store_dwordx2 v[6:7], v[8:9] offset:32
	v_pk_mul_f32 v[8:9], v[72:73], v[4:5] op_sel_hi:[1,0]
	v_pk_mul_f32 v[10:11], v[74:75], v[4:5] op_sel_hi:[1,0]
	v_cvt_pk_bf16_f32 v8, v8, v9
	v_cvt_pk_bf16_f32 v9, v10, v11
	flat_store_dwordx2 v[6:7], v[8:9] offset:64
	v_pk_mul_f32 v[8:9], v[76:77], v[4:5] op_sel_hi:[1,0]
	v_mov_b32_e32 v5, v100
	s_nop 1
	v_permlane16_swap_b32_e32 v100, v5
	v_add_f32_e32 v5, v100, v5
	v_cvt_pk_bf16_f32 v8, v8, v9
	v_mov_b32_e32 v9, v5
	s_nop 1
	v_permlane32_swap_b32_e32 v5, v9
	v_add_f32_e32 v10, v5, v9
	v_div_scale_f32 v11, s[6:7], v10, v10, 1.0
	v_rcp_f32_e32 v12, v11
	v_pk_mul_f32 v[4:5], v[78:79], v[4:5] op_sel_hi:[1,0]
	s_nop 0
	v_cvt_pk_bf16_f32 v9, v4, v5
	v_fma_f32 v4, -v11, v12, 1.0
	v_fmac_f32_e32 v12, v4, v12
	v_div_scale_f32 v4, vcc, 1.0, v10, 1.0
	v_mul_f32_e32 v5, v4, v12
	flat_store_dwordx2 v[6:7], v[8:9] offset:96
	v_fma_f32 v6, -v11, v5, v4
	v_fmac_f32_e32 v5, v6, v12
	v_fma_f32 v4, -v11, v5, v4
	v_div_fmas_f32 v4, v4, v12, v5
	v_lshlrev_b64 v[6:7], 11, v[90:91]
	v_div_fixup_f32 v4, v4, v10, 1.0
	v_lshl_add_u64 v[6:7], s[48:49], 0, v[6:7]
	v_lshl_add_u64 v[6:7], v[6:7], 0, s[44:45]
	v_pk_mul_f32 v[8:9], v[52:53], v[4:5] op_sel_hi:[1,0]
	v_pk_mul_f32 v[10:11], v[54:55], v[4:5] op_sel_hi:[1,0]
	v_lshl_add_u64 v[6:7], v[6:7], 0, v[88:89]
	v_cvt_pk_bf16_f32 v8, v8, v9
	v_cvt_pk_bf16_f32 v9, v10, v11
	flat_store_dwordx2 v[6:7], v[8:9]
	v_pk_mul_f32 v[8:9], v[48:49], v[4:5] op_sel_hi:[1,0]
	v_pk_mul_f32 v[10:11], v[50:51], v[4:5] op_sel_hi:[1,0]
	v_cvt_pk_bf16_f32 v8, v8, v9
	v_cvt_pk_bf16_f32 v9, v10, v11
	flat_store_dwordx2 v[6:7], v[8:9] offset:32
	v_pk_mul_f32 v[8:9], v[56:57], v[4:5] op_sel_hi:[1,0]
	v_pk_mul_f32 v[10:11], v[58:59], v[4:5] op_sel_hi:[1,0]
	v_cvt_pk_bf16_f32 v8, v8, v9
	v_cvt_pk_bf16_f32 v9, v10, v11
	flat_store_dwordx2 v[6:7], v[8:9] offset:64
	v_pk_mul_f32 v[8:9], v[60:61], v[4:5] op_sel_hi:[1,0]
	v_pk_mul_f32 v[4:5], v[62:63], v[4:5] op_sel_hi:[1,0]
	v_cvt_pk_bf16_f32 v8, v8, v9
	v_cvt_pk_bf16_f32 v9, v4, v5
	flat_store_dwordx2 v[6:7], v[8:9] offset:96
	s_waitcnt lgkmcnt(0)
	s_barrier
	s_and_saveexec_b64 s[6:7], s[4:5]
	s_cbranch_execz .LBB0_1198
	s_cmp_eq_u32 s32, 0
	s_cbranch_scc1 .Lqf0
	s_waitcnt vmcnt(0) lgkmcnt(0)
	ds_write_b32 v178, v253
	s_mov_b32 s32, 0
	s_branch .LBB0_1198
.Lqf0:
	v_readlane_b32 s2, v252, 23
	v_readlane_b32 s3, v252, 24
	s_nop 1
	v_mov_b64_e32 v[4:5], s[2:3]
	flat_atomic_add v4, v[4:5], v177 sc0
	s_waitcnt vmcnt(0) lgkmcnt(0)
	ds_write_b32 v178, v4
	s_branch .LBB0_1198

.LBB0_1223:
	s_cmp_lt_i32 s10, 64
	s_cbranch_scc1 .Lqe1
	s_mov_b64 s[98:99], exec
	s_mov_b64 exec, s[4:5]
	s_cbranch_execz .Lqp1
	v_readlane_b32 s8, v252, 23
	v_readlane_b32 s9, v252, 24
	s_nop 1
	v_mov_b64_e32 v[254:255], s[8:9]
	global_atomic_add v253, v[254:255], v177, off sc0
.Lqp1:
	s_mov_b64 exec, s[98:99]
	s_mov_b32 s32, 1

.LBB0_1241:
	s_waitcnt lgkmcnt(0)
	s_barrier
	s_and_saveexec_b64 s[6:7], s[4:5]
	s_cbranch_execz .LBB0_1222
	s_cmp_eq_u32 s32, 0
	s_cbranch_scc1 .Lqf1
	s_waitcnt vmcnt(0) lgkmcnt(0)
	ds_write_b32 v178, v253
	s_mov_b32 s32, 0
	s_branch .LBB0_1222

.LBB0_1282:
	s_barrier
	s_and_saveexec_b64 s[6:7], s[4:5]
	s_cbranch_execz .LBB0_1243
	s_cmp_eq_u32 s32, 0
	s_cbranch_scc1 .Lqf2
	s_waitcnt vmcnt(0) lgkmcnt(0)
	ds_write_b32 v178, v253
	s_mov_b32 s32, 0
	s_branch .LBB0_1243

.LBB0_1285:
	s_cmpk_ge_i32 s10, 0x120
	s_cbranch_scc1 .Lqe2
	s_mov_b64 s[98:99], exec
	s_mov_b64 exec, s[4:5]
	s_cbranch_execz .Lqp2
	v_readlane_b32 s8, v252, 23
	v_readlane_b32 s9, v252, 24
	s_nop 1
	v_mov_b64_e32 v[254:255], s[8:9]
	global_atomic_add v253, v[254:255], v177, off sc0

.LBB0_1312:
	v_mov_b32_e32 v4, v97
	s_nop 1
	v_permlane16_swap_b32_e32 v97, v4
	v_add_f32_e32 v4, v97, v4
	v_mov_b32_e32 v5, v4
	s_nop 1
	v_permlane32_swap_b32_e32 v4, v5
	v_add_f32_e32 v4, v4, v5
	v_div_scale_f32 v5, s[6:7], v4, v4, 1.0
	v_rcp_f32_e32 v6, v5
	v_mov_b32_e32 v103, v89
	s_lshl_b32 s44, s94, 1
	s_mov_b64 s[8:9], 0x4552200
	v_fma_f32 v7, -v5, v6, 1.0
	v_fmac_f32_e32 v6, v7, v6
	v_div_scale_f32 v7, vcc, 1.0, v4, 1.0
	v_mul_f32_e32 v8, v7, v6
	v_fma_f32 v9, -v5, v8, v7
	v_fmac_f32_e32 v8, v9, v6
	v_fma_f32 v5, -v5, v8, v7
	v_div_fmas_f32 v5, v5, v6, v8
	v_lshlrev_b64 v[6:7], 11, v[92:93]
	v_lshl_add_u64 v[6:7], s[42:43], 0, v[6:7]
	v_lshl_add_u64 v[6:7], v[6:7], 0, s[44:45]
	v_lshlrev_b64 v[8:9], 1, v[102:103]
	v_div_fixup_f32 v4, v5, v4, 1.0
	v_lshl_add_u64 v[6:7], v[6:7], 0, v[8:9]
	s_mov_b32 s2, 0x4552000
	v_lshl_add_u64 v[10:11], v[6:7], 0, s[8:9]
	v_pk_mul_f32 v[12:13], v[56:57], v[4:5] op_sel_hi:[1,0]
	v_pk_mul_f32 v[14:15], v[58:59], v[4:5] op_sel_hi:[1,0]
	v_add_co_u32_e32 v6, vcc, s2, v6
	v_cvt_pk_bf16_f32 v12, v12, v13
	v_cvt_pk_bf16_f32 v13, v14, v15
	v_addc_co_u32_e32 v7, vcc, 0, v7, vcc
	flat_store_dwordx2 v[6:7], v[12:13] offset:512
	v_pk_mul_f32 v[6:7], v[52:53], v[4:5] op_sel_hi:[1,0]
	v_pk_mul_f32 v[12:13], v[54:55], v[4:5] op_sel_hi:[1,0]
	v_cvt_pk_bf16_f32 v6, v6, v7
	v_cvt_pk_bf16_f32 v7, v12, v13
	flat_store_dwordx2 v[10:11], v[6:7] offset:32
	v_pk_mul_f32 v[6:7], v[60:61], v[4:5] op_sel_hi:[1,0]
	v_pk_mul_f32 v[12:13], v[62:63], v[4:5] op_sel_hi:[1,0]
	v_cvt_pk_bf16_f32 v6, v6, v7
	v_cvt_pk_bf16_f32 v7, v12, v13
	flat_store_dwordx2 v[10:11], v[6:7] offset:64
	v_pk_mul_f32 v[6:7], v[64:65], v[4:5] op_sel_hi:[1,0]
	v_mov_b32_e32 v5, v96
	s_nop 1
	v_permlane16_swap_b32_e32 v96, v5
	v_add_f32_e32 v5, v96, v5
	v_cvt_pk_bf16_f32 v6, v6, v7
	v_mov_b32_e32 v7, v5
	s_nop 1
	v_permlane32_swap_b32_e32 v5, v7
	v_add_f32_e32 v12, v5, v7
	v_div_scale_f32 v13, s[6:7], v12, v12, 1.0
	v_rcp_f32_e32 v14, v13
	v_pk_mul_f32 v[4:5], v[66:67], v[4:5] op_sel_hi:[1,0]
	s_mov_b64 s[92:93], s[68:69]
	v_cvt_pk_bf16_f32 v7, v4, v5
	v_fma_f32 v4, -v13, v14, 1.0
	v_fmac_f32_e32 v14, v4, v14
	v_div_scale_f32 v4, vcc, 1.0, v12, 1.0
	v_mul_f32_e32 v5, v4, v14
	flat_store_dwordx2 v[10:11], v[6:7] offset:96
	v_fma_f32 v6, -v13, v5, v4
	v_fmac_f32_e32 v5, v6, v14
	v_lshlrev_b64 v[6:7], 11, v[90:91]
	v_fma_f32 v4, -v13, v5, v4
	v_lshl_add_u64 v[6:7], s[42:43], 0, v[6:7]
	v_div_fmas_f32 v4, v4, v14, v5
	v_lshl_add_u64 v[6:7], v[6:7], 0, s[44:45]
	v_div_fixup_f32 v4, v4, v12, 1.0
	v_lshl_add_u64 v[6:7], v[6:7], 0, v[8:9]
	v_lshl_add_u64 v[8:9], v[6:7], 0, s[8:9]
	v_pk_mul_f32 v[10:11], v[40:41], v[4:5] op_sel_hi:[1,0]
	v_pk_mul_f32 v[12:13], v[42:43], v[4:5] op_sel_hi:[1,0]
	v_add_co_u32_e32 v6, vcc, s2, v6
	v_cvt_pk_bf16_f32 v10, v10, v11
	v_cvt_pk_bf16_f32 v11, v12, v13
	v_addc_co_u32_e32 v7, vcc, 0, v7, vcc
	flat_store_dwordx2 v[6:7], v[10:11] offset:512
	v_pk_mul_f32 v[6:7], v[36:37], v[4:5] op_sel_hi:[1,0]
	v_pk_mul_f32 v[10:11], v[38:39], v[4:5] op_sel_hi:[1,0]
	v_cvt_pk_bf16_f32 v6, v6, v7
	v_cvt_pk_bf16_f32 v7, v10, v11
	flat_store_dwordx2 v[8:9], v[6:7] offset:32
	v_pk_mul_f32 v[6:7], v[44:45], v[4:5] op_sel_hi:[1,0]
	v_pk_mul_f32 v[10:11], v[46:47], v[4:5] op_sel_hi:[1,0]
	v_cvt_pk_bf16_f32 v6, v6, v7
	v_cvt_pk_bf16_f32 v7, v10, v11
	flat_store_dwordx2 v[8:9], v[6:7] offset:64
	v_pk_mul_f32 v[6:7], v[48:49], v[4:5] op_sel_hi:[1,0]
	v_pk_mul_f32 v[4:5], v[50:51], v[4:5] op_sel_hi:[1,0]
	v_cvt_pk_bf16_f32 v6, v6, v7
	v_cvt_pk_bf16_f32 v7, v4, v5
	flat_store_dwordx2 v[8:9], v[6:7] offset:96
	s_waitcnt lgkmcnt(0)
	s_barrier
	s_and_saveexec_b64 s[6:7], s[4:5]
	s_cbranch_execz .LBB0_1284
	s_cmp_eq_u32 s32, 0
	s_cbranch_scc1 .Lqf3
	s_waitcnt vmcnt(0) lgkmcnt(0)
	ds_write_b32 v178, v253
	s_mov_b32 s32, 0
	s_branch .LBB0_1284

.LBB0_2950:
	s_mov_b32 s32, 0
	v_readlane_b32 s8, v252, 7
	v_readlane_b32 s9, v252, 8
	s_and_b64 s[8:9], s[8:9], s[14:15]
	s_and_b64 vcc, exec, s[8:9]
	s_mov_b32 s10, -1
	s_cbranch_vccnz .LBB0_2954
	s_barrier
	s_and_saveexec_b64 s[8:9], s[4:5]
	s_cbranch_execz .LBB0_2953
	s_lshl_b64 s[10:11], s[6:7], 2
	v_readlane_b32 s12, v252, 11
	s_add_u32 s10, s12, s10
	v_readlane_b32 s12, v252, 12
	s_addc_u32 s11, s12, s11
	v_mov_b64_e32 v[4:5], s[10:11]
	flat_atomic_add v4, v[4:5], v176 sc0
	s_waitcnt vmcnt(0) lgkmcnt(0)
	ds_write_b32 v177, v4

.LBB0_2973:
	s_mov_b64 s[98:99], exec
	s_mov_b64 exec, s[4:5]
	s_cbranch_execz .Lqp7
	v_readlane_b32 s8, v252, 23
	v_readlane_b32 s9, v252, 24
	s_nop 1
	v_mov_b64_e32 v[254:255], s[8:9]
	global_atomic_add v253, v[254:255], v176, off sc0

.Lqe7:
	v_mov_b32_e32 v4, v101
	s_nop 1
	v_permlane16_swap_b32_e32 v101, v4
	v_add_f32_e32 v4, v101, v4
	v_mov_b32_e32 v5, v4
	s_nop 1
	v_permlane32_swap_b32_e32 v4, v5
	v_add_f32_e32 v4, v4, v5
	v_div_scale_f32 v5, s[6:7], v4, v4, 1.0
	v_rcp_f32_e32 v6, v5
	v_lshlrev_b32_e32 v88, 1, v97
	v_fma_f32 v7, -v5, v6, 1.0
	v_fmac_f32_e32 v6, v7, v6
	v_div_scale_f32 v7, vcc, 1.0, v4, 1.0
	v_mul_f32_e32 v8, v7, v6
	v_fma_f32 v9, -v5, v8, v7
	v_fmac_f32_e32 v8, v9, v6
	v_fma_f32 v5, -v5, v8, v7
	v_div_fmas_f32 v5, v5, v6, v8
	v_lshlrev_b64 v[6:7], 11, v[92:93]
	v_div_fixup_f32 v4, v5, v4, 1.0
	v_lshl_add_u64 v[6:7], s[48:49], 0, v[6:7]
	v_lshl_add_u64 v[6:7], v[6:7], 0, s[44:45]
	v_pk_mul_f32 v[8:9], v[68:69], v[4:5] op_sel_hi:[1,0]
	v_pk_mul_f32 v[10:11], v[70:71], v[4:5] op_sel_hi:[1,0]
	v_lshl_add_u64 v[6:7], v[6:7], 0, v[88:89]
	v_cvt_pk_bf16_f32 v8, v8, v9
	v_cvt_pk_bf16_f32 v9, v10, v11
	flat_store_dwordx2 v[6:7], v[8:9]
	v_pk_mul_f32 v[8:9], v[64:65], v[4:5] op_sel_hi:[1,0]
	v_pk_mul_f32 v[10:11], v[66:67], v[4:5] op_sel_hi:[1,0]
	v_cvt_pk_bf16_f32 v8, v8, v9
	v_cvt_pk_bf16_f32 v9, v10, v11
	flat_store_dwordx2 v[6:7], v[8:9] offset:32
	v_pk_mul_f32 v[8:9], v[72:73], v[4:5] op_sel_hi:[1,0]
	v_pk_mul_f32 v[10:11], v[74:75], v[4:5] op_sel_hi:[1,0]
	v_cvt_pk_bf16_f32 v8, v8, v9
	v_cvt_pk_bf16_f32 v9, v10, v11
	flat_store_dwordx2 v[6:7], v[8:9] offset:64
	v_pk_mul_f32 v[8:9], v[76:77], v[4:5] op_sel_hi:[1,0]
	v_mov_b32_e32 v5, v100
	s_nop 1
	v_permlane16_swap_b32_e32 v100, v5
	v_add_f32_e32 v5, v100, v5
	v_cvt_pk_bf16_f32 v8, v8, v9
	v_mov_b32_e32 v9, v5
	s_nop 1
	v_permlane32_swap_b32_e32 v5, v9
	v_add_f32_e32 v10, v5, v9
	v_div_scale_f32 v11, s[6:7], v10, v10, 1.0
	v_rcp_f32_e32 v12, v11
	v_pk_mul_f32 v[4:5], v[78:79], v[4:5] op_sel_hi:[1,0]
	s_nop 0
	v_cvt_pk_bf16_f32 v9, v4, v5
	v_fma_f32 v4, -v11, v12, 1.0
	v_fmac_f32_e32 v12, v4, v12
	v_div_scale_f32 v4, vcc, 1.0, v10, 1.0
	v_mul_f32_e32 v5, v4, v12
	flat_store_dwordx2 v[6:7], v[8:9] offset:96
	v_fma_f32 v6, -v11, v5, v4
	v_fmac_f32_e32 v5, v6, v12
	v_fma_f32 v4, -v11, v5, v4
	v_div_fmas_f32 v4, v4, v12, v5
	v_lshlrev_b64 v[6:7], 11, v[90:91]
	v_div_fixup_f32 v4, v4, v10, 1.0
	v_lshl_add_u64 v[6:7], s[48:49], 0, v[6:7]
	v_lshl_add_u64 v[6:7], v[6:7], 0, s[44:45]
	v_pk_mul_f32 v[8:9], v[52:53], v[4:5] op_sel_hi:[1,0]
	v_pk_mul_f32 v[10:11], v[54:55], v[4:5] op_sel_hi:[1,0]
	v_lshl_add_u64 v[6:7], v[6:7], 0, v[88:89]
	v_cvt_pk_bf16_f32 v8, v8, v9
	v_cvt_pk_bf16_f32 v9, v10, v11
	flat_store_dwordx2 v[6:7], v[8:9]
	v_pk_mul_f32 v[8:9], v[48:49], v[4:5] op_sel_hi:[1,0]
	v_pk_mul_f32 v[10:11], v[50:51], v[4:5] op_sel_hi:[1,0]
	v_cvt_pk_bf16_f32 v8, v8, v9
	v_cvt_pk_bf16_f32 v9, v10, v11
	flat_store_dwordx2 v[6:7], v[8:9] offset:32
	v_pk_mul_f32 v[8:9], v[56:57], v[4:5] op_sel_hi:[1,0]
	v_pk_mul_f32 v[10:11], v[58:59], v[4:5] op_sel_hi:[1,0]
	v_cvt_pk_bf16_f32 v8, v8, v9
	v_cvt_pk_bf16_f32 v9, v10, v11
	flat_store_dwordx2 v[6:7], v[8:9] offset:64
	v_pk_mul_f32 v[8:9], v[60:61], v[4:5] op_sel_hi:[1,0]
	v_pk_mul_f32 v[4:5], v[62:63], v[4:5] op_sel_hi:[1,0]
	v_cvt_pk_bf16_f32 v8, v8, v9
	v_cvt_pk_bf16_f32 v9, v4, v5
	flat_store_dwordx2 v[6:7], v[8:9] offset:96
	s_waitcnt lgkmcnt(0)
	s_barrier
	s_and_saveexec_b64 s[6:7], s[4:5]
	s_cbranch_execz .LBB0_2955
	s_cmp_eq_u32 s32, 0
	s_cbranch_scc1 .Lqf5
	s_waitcnt vmcnt(0) lgkmcnt(0)
	ds_write_b32 v177, v253
	s_mov_b32 s32, 0
	s_branch .LBB0_2955
.Lqf5:
	v_readlane_b32 s8, v252, 23
	v_readlane_b32 s9, v252, 24
	s_nop 1
	v_mov_b64_e32 v[4:5], s[8:9]
	flat_atomic_add v4, v[4:5], v176 sc0
	s_waitcnt vmcnt(0) lgkmcnt(0)
	ds_write_b32 v177, v4
	s_branch .LBB0_2955

.LBB0_2980:
	s_cmp_lt_i32 s10, 64
	s_cbranch_scc1 .Lqe5
	s_mov_b64 s[98:99], exec
	s_mov_b64 exec, s[4:5]
	s_cbranch_execz .Lqp5
	v_readlane_b32 s8, v252, 23
	v_readlane_b32 s9, v252, 24
	s_nop 1
	v_mov_b64_e32 v[254:255], s[8:9]
	global_atomic_add v253, v[254:255], v176, off sc0

.LBB0_2998:
	s_waitcnt lgkmcnt(0)
	s_barrier
	s_and_saveexec_b64 s[6:7], s[4:5]
	s_cbranch_execz .LBB0_2979
	s_cmp_eq_u32 s32, 0
	s_cbranch_scc1 .Lqf6
	s_waitcnt vmcnt(0) lgkmcnt(0)
	ds_write_b32 v177, v253
	s_mov_b32 s32, 0
	s_branch .LBB0_2979

.LBB0_3039:
	s_barrier
	s_and_saveexec_b64 s[6:7], s[4:5]
	s_cbranch_execz .LBB0_3000
	s_cmp_eq_u32 s32, 0
	s_cbranch_scc1 .Lqf7
	s_waitcnt vmcnt(0) lgkmcnt(0)
	ds_write_b32 v177, v253
	s_mov_b32 s32, 0
	s_branch .LBB0_3000

.LBB0_3042:
	s_cmpk_ge_i32 s10, 0x120
	s_cbranch_scc1 .Lqe6
	s_mov_b64 s[98:99], exec
	s_mov_b64 exec, s[4:5]
	s_cbranch_execz .Lqp6
	v_readlane_b32 s8, v252, 23
	v_readlane_b32 s9, v252, 24
	s_nop 1
	v_mov_b64_e32 v[254:255], s[8:9]
	global_atomic_add v253, v[254:255], v176, off sc0

.LBB0_3069:
	v_mov_b32_e32 v4, v97
	s_nop 1
	v_permlane16_swap_b32_e32 v97, v4
	v_add_f32_e32 v4, v97, v4
	v_mov_b32_e32 v5, v4
	s_nop 1
	v_permlane32_swap_b32_e32 v4, v5
	v_add_f32_e32 v4, v4, v5
	v_div_scale_f32 v5, s[6:7], v4, v4, 1.0
	v_rcp_f32_e32 v6, v5
	v_mov_b32_e32 v105, v89
	s_lshl_b32 s44, s78, 1
	s_mov_b64 s[76:77], s[66:67]
	v_fma_f32 v7, -v5, v6, 1.0
	v_fmac_f32_e32 v6, v7, v6
	v_div_scale_f32 v7, vcc, 1.0, v4, 1.0
	v_mul_f32_e32 v8, v7, v6
	v_fma_f32 v9, -v5, v8, v7
	v_fmac_f32_e32 v8, v9, v6
	v_fma_f32 v5, -v5, v8, v7
	v_div_fmas_f32 v5, v5, v6, v8
	v_lshlrev_b64 v[6:7], 11, v[92:93]
	v_lshl_add_u64 v[6:7], s[42:43], 0, v[6:7]
	v_lshl_add_u64 v[6:7], v[6:7], 0, s[44:45]
	v_lshlrev_b64 v[8:9], 1, v[104:105]
	v_div_fixup_f32 v4, v5, v4, 1.0
	v_lshl_add_u64 v[6:7], v[6:7], 0, v[8:9]
	v_lshl_add_u64 v[10:11], v[6:7], 0, s[96:97]
	v_pk_mul_f32 v[12:13], v[56:57], v[4:5] op_sel_hi:[1,0]
	v_pk_mul_f32 v[14:15], v[58:59], v[4:5] op_sel_hi:[1,0]
	v_add_co_u32_e32 v6, vcc, s94, v6
	v_cvt_pk_bf16_f32 v12, v12, v13
	v_cvt_pk_bf16_f32 v13, v14, v15
	v_addc_co_u32_e32 v7, vcc, 0, v7, vcc
	flat_store_dwordx2 v[6:7], v[12:13] offset:512
	v_pk_mul_f32 v[6:7], v[52:53], v[4:5] op_sel_hi:[1,0]
	v_pk_mul_f32 v[12:13], v[54:55], v[4:5] op_sel_hi:[1,0]
	v_cvt_pk_bf16_f32 v6, v6, v7
	v_cvt_pk_bf16_f32 v7, v12, v13
	flat_store_dwordx2 v[10:11], v[6:7] offset:32
	v_pk_mul_f32 v[6:7], v[60:61], v[4:5] op_sel_hi:[1,0]
	v_pk_mul_f32 v[12:13], v[62:63], v[4:5] op_sel_hi:[1,0]
	v_cvt_pk_bf16_f32 v6, v6, v7
	v_cvt_pk_bf16_f32 v7, v12, v13
	flat_store_dwordx2 v[10:11], v[6:7] offset:64
	v_pk_mul_f32 v[6:7], v[64:65], v[4:5] op_sel_hi:[1,0]
	v_mov_b32_e32 v5, v96
	s_nop 1
	v_permlane16_swap_b32_e32 v96, v5
	v_add_f32_e32 v5, v96, v5
	v_cvt_pk_bf16_f32 v6, v6, v7
	v_mov_b32_e32 v7, v5
	s_nop 1
	v_permlane32_swap_b32_e32 v5, v7
	v_add_f32_e32 v12, v5, v7
	v_div_scale_f32 v13, s[6:7], v12, v12, 1.0
	v_rcp_f32_e32 v14, v13
	v_pk_mul_f32 v[4:5], v[66:67], v[4:5] op_sel_hi:[1,0]
	s_nop 0
	v_cvt_pk_bf16_f32 v7, v4, v5
	v_fma_f32 v4, -v13, v14, 1.0
	v_fmac_f32_e32 v14, v4, v14
	v_div_scale_f32 v4, vcc, 1.0, v12, 1.0
	v_mul_f32_e32 v5, v4, v14
	flat_store_dwordx2 v[10:11], v[6:7] offset:96
	v_fma_f32 v6, -v13, v5, v4
	v_fmac_f32_e32 v5, v6, v14
	v_lshlrev_b64 v[6:7], 11, v[90:91]
	v_fma_f32 v4, -v13, v5, v4
	v_lshl_add_u64 v[6:7], s[42:43], 0, v[6:7]
	v_div_fmas_f32 v4, v4, v14, v5
	v_lshl_add_u64 v[6:7], v[6:7], 0, s[44:45]
	v_div_fixup_f32 v4, v4, v12, 1.0
	v_lshl_add_u64 v[6:7], v[6:7], 0, v[8:9]
	v_lshl_add_u64 v[8:9], v[6:7], 0, s[96:97]
	v_pk_mul_f32 v[10:11], v[40:41], v[4:5] op_sel_hi:[1,0]
	v_pk_mul_f32 v[12:13], v[42:43], v[4:5] op_sel_hi:[1,0]
	v_add_co_u32_e32 v6, vcc, s94, v6
	v_cvt_pk_bf16_f32 v10, v10, v11
	v_cvt_pk_bf16_f32 v11, v12, v13
	v_addc_co_u32_e32 v7, vcc, 0, v7, vcc
	flat_store_dwordx2 v[6:7], v[10:11] offset:512
	v_pk_mul_f32 v[6:7], v[36:37], v[4:5] op_sel_hi:[1,0]
	v_pk_mul_f32 v[10:11], v[38:39], v[4:5] op_sel_hi:[1,0]
	v_cvt_pk_bf16_f32 v6, v6, v7
	v_cvt_pk_bf16_f32 v7, v10, v11
	flat_store_dwordx2 v[8:9], v[6:7] offset:32
	v_pk_mul_f32 v[6:7], v[44:45], v[4:5] op_sel_hi:[1,0]
	v_pk_mul_f32 v[10:11], v[46:47], v[4:5] op_sel_hi:[1,0]
	v_cvt_pk_bf16_f32 v6, v6, v7
	v_cvt_pk_bf16_f32 v7, v10, v11
	flat_store_dwordx2 v[8:9], v[6:7] offset:64
	v_pk_mul_f32 v[6:7], v[48:49], v[4:5] op_sel_hi:[1,0]
	v_pk_mul_f32 v[4:5], v[50:51], v[4:5] op_sel_hi:[1,0]
	v_cvt_pk_bf16_f32 v6, v6, v7
	v_cvt_pk_bf16_f32 v7, v4, v5
	flat_store_dwordx2 v[8:9], v[6:7] offset:96
	s_waitcnt lgkmcnt(0)
	s_barrier
	s_and_saveexec_b64 s[6:7], s[4:5]
	s_cbranch_execz .LBB0_3041
	s_cmp_eq_u32 s32, 0
	s_cbranch_scc1 .Lqf8
	s_waitcnt vmcnt(0) lgkmcnt(0)
	ds_write_b32 v177, v253
	s_mov_b32 s32, 0
	s_branch .LBB0_3041

	.amdhsa_kernel _Z12trunk_kernel2KP
		.amdhsa_group_segment_fixed_size 131088
		.amdhsa_private_segment_fixed_size 0
		.amdhsa_kernarg_size 576
		.amdhsa_user_sgpr_count 2
		.amdhsa_user_sgpr_dispatch_ptr 0
		.amdhsa_user_sgpr_queue_ptr 0
		.amdhsa_user_sgpr_kernarg_segment_ptr 1
		.amdhsa_user_sgpr_dispatch_id 0
		.amdhsa_user_sgpr_kernarg_preload_length 0
		.amdhsa_user_sgpr_kernarg_preload_offset 0
		.amdhsa_user_sgpr_private_segment_size 0
		.amdhsa_uses_dynamic_stack 0
		.amdhsa_enable_private_segment 0
		.amdhsa_system_sgpr_workgroup_id_x 1
		.amdhsa_system_sgpr_workgroup_id_y 0
		.amdhsa_system_sgpr_workgroup_id_z 0
		.amdhsa_system_sgpr_workgroup_info 0
		.amdhsa_system_vgpr_workitem_id 2
		.amdhsa_next_free_vgpr 256
		.amdhsa_next_free_sgpr 100
		.amdhsa_accum_offset 256
		.amdhsa_reserve_vcc 1
		.amdhsa_float_round_mode_32 0
		.amdhsa_float_round_mode_16_64 0
		.amdhsa_float_denorm_mode_32 3
		.amdhsa_float_denorm_mode_16_64 3
		.amdhsa_dx10_clamp 1
		.amdhsa_ieee_mode 1
		.amdhsa_fp16_overflow 0
		.amdhsa_tg_split 0
		.amdhsa_exception_fp_ieee_invalid_op 0
		.amdhsa_exception_fp_denorm_src 0
		.amdhsa_exception_fp_ieee_div_zero 0
		.amdhsa_exception_fp_ieee_overflow 0
		.amdhsa_exception_fp_ieee_underflow 0
		.amdhsa_exception_fp_ieee_inexact 0
		.amdhsa_exception_int_div_zero 0
	.end_amdhsa_kernel

amdhsa.kernels:
  - .agpr_count:     0
    .args:
      - .offset:         0
        .size:           320
        .value_kind:     by_value
      - .offset:         320
        .size:           4
        .value_kind:     hidden_block_count_x
      - .offset:         324
        .size:           4
        .value_kind:     hidden_block_count_y
      - .offset:         328
        .size:           4
        .value_kind:     hidden_block_count_z
      - .offset:         332
        .size:           2
        .value_kind:     hidden_group_size_x
      - .offset:         334
        .size:           2
        .value_kind:     hidden_group_size_y
      - .offset:         336
        .size:           2
        .value_kind:     hidden_group_size_z
      - .offset:         338
        .size:           2
        .value_kind:     hidden_remainder_x
      - .offset:         340
        .size:           2
        .value_kind:     hidden_remainder_y
      - .offset:         342
        .size:           2
        .value_kind:     hidden_remainder_z
      - .offset:         360
        .size:           8
        .value_kind:     hidden_global_offset_x
      - .offset:         368
        .size:           8
        .value_kind:     hidden_global_offset_y
      - .offset:         376
        .size:           8
        .value_kind:     hidden_global_offset_z
      - .offset:         384
        .size:           2
        .value_kind:     hidden_grid_dims
      - .offset:         408
        .size:           8
        .value_kind:     hidden_multigrid_sync_arg
    .group_segment_fixed_size: 131088
    .kernarg_segment_align: 8
    .kernarg_segment_size: 576
    .language:       OpenCL C
    .language_version:
      - 2
      - 0
    .max_flat_workgroup_size: 512
    .name:           _Z12trunk_kernel2KP
    .private_segment_fixed_size: 0
    .sgpr_count:     106
    .sgpr_spill_count: 45
    .symbol:         _Z12trunk_kernel2KP.kd
    .uniform_work_group_size: 1
    .uses_dynamic_stack: false
    .vgpr_count:     256
    .vgpr_spill_count: 0
    .wavefront_size: 64
